# gate/up K loop: first two counted waits of each tile (after the first) leave the previous tile's 16 epilogue stores in flight (vmcnt(24) instead of vmcnt(8))
# baseline (speedup 1.0000x reference)
; #define PG8_STAGE(bufoff, gbase, voff) do { _Pragma("unroll") for (int _i = 0; _i < 2; ++_i) \
;         __builtin_amdgcn_global_load_lds((const unsigned*)((const char*)(gbase) + (voff)[_i]), (LAS unsigned*)(lds + (bufoff) + ldsw + _i * 8192), 16, 0, 0); } while (0)
; #define PG8_WAIT_V(n) asm volatile("s_waitcnt vmcnt(" #n ")" ::: "memory")
; #define PG8_WAIT_L(n) asm volatile("s_waitcnt lgkmcnt(" #n ")" ::: "memory")
; #define PG8_BAR __builtin_amdgcn_s_barrier()
; #define PG8_SCHED __builtin_amdgcn_sched_barrier(0)
; template <bool GATHER, bool FP8, class Epi, class Sched>
; __device__ __forceinline__ void gemm_phase(LAS unsigned char* lds, const int tid, const int K, const Sched& S, const Epi& E) {
;     ...
;             PG8_LDB(B0, 0, 0); PG8_LDB(B1, 0, 1); PG8_SCHED; PG8_LDA(At, 0, 0); PG8_STAGE(PG8_SA(1, 1), a1 + hsA, oC[1]);
;             PG8_WAIT_V(8); PG8_WAIT_L(0); PG8_BAR; PG8_MMA(0, 0, At, B0); PG8_MMA(0, 1, At, B1); PG8_BAR; PG8_SCHED;
;             PG8_LDA(At, 0, 1); PG8_STAGE(PG8_SB(0, 0), b2, voffB); PG8_STAGE(PG8_SB(0, 1), b2 + hstepB, voffB); PG8_STAGE(PG8_SA(0, 0), a2, o2[0]);
;             PG8_WAIT_V(8); PG8_WAIT_L(0); PG8_BAR; PG8_MMA(1, 0, At, B0); PG8_MMA(1, 1, At, B1); PG8_BAR; PG8_SCHED;
.LBB0_94:
	ds_read_b128 v[16:19], v191
	ds_read_b128 v[20:23], v192
	ds_read_b128 v[24:27], v194
	ds_read_b128 v[28:31], v195
	ds_read_b128 v[0:3], v196
	ds_read_b128 v[4:7], v197
	ds_read_b128 v[8:11], v212
	ds_read_b128 v[12:15], v213
	s_add_u32 s26, s20, 0x80
	s_addc_u32 s27, s21, 0
	s_and_b64 s[22:23], s[22:23], exec
	s_cselect_b32 s27, s7, s27
	s_cselect_b32 s26, s6, s26
	s_cselect_b32 s23, s41, s12
	s_cselect_b32 s22, s51, s17
	v_lshl_add_u64 v[182:183], s[20:21], 0, v[178:179]
	s_add_i32 m0, s47, 0xc000
	ds_read_b128 v[224:227], v222
	ds_read_b128 v[228:231], v222 offset:1024
	ds_read_b128 v[232:235], v222 offset:2048
	ds_read_b128 v[236:239], v222 offset:3072
	ds_read_b128 v[240:243], v222 offset:4096
	ds_read_b128 v[244:247], v222 offset:5120
	ds_read_b128 v[198:201], v222 offset:6144
	ds_read_b128 v[202:205], v222 offset:7168
	global_load_lds_dwordx4 v[182:183], off
	v_lshl_add_u64 v[182:183], s[20:21], 0, v[180:181]
	s_add_i32 m0, s47, 0xe000
	s_nop 0
	global_load_lds_dwordx4 v[182:183], off
	s_cmp_lg_i32 s71, -2
	s_cbranch_scc1 .Lgw0_steady
	s_cmp_eq_u32 s95, 0
	s_cbranch_scc1 .Lgw0_steady
	s_waitcnt vmcnt(24)
	s_branch .Lgw0_done
.Lgw0_steady:
	s_waitcnt vmcnt(8)
.Lgw0_done:
	s_waitcnt lgkmcnt(0)
	s_barrier
	s_setprio 1
	s_waitcnt lgkmcnt(0)
	v_mfma_scale_f32_16x16x128_f8f6f4 v[160:163], v[16:23], v[224:231], v[160:163], v169, v169 op_sel_hi:[0,0,0]
	v_mfma_scale_f32_16x16x128_f8f6f4 v[156:159], v[24:31], v[224:231], v[156:159], v169, v169 op_sel_hi:[0,0,0]
	v_mfma_scale_f32_16x16x128_f8f6f4 v[144:147], v[16:23], v[232:239], v[144:147], v169, v169 op_sel_hi:[0,0,0]
	v_mfma_scale_f32_16x16x128_f8f6f4 v[140:143], v[24:31], v[232:239], v[140:143], v169, v169 op_sel_hi:[0,0,0]
	v_mfma_scale_f32_16x16x128_f8f6f4 v[128:131], v[16:23], v[240:247], v[128:131], v169, v169 op_sel_hi:[0,0,0]
	v_mfma_scale_f32_16x16x128_f8f6f4 v[124:127], v[24:31], v[240:247], v[124:127], v169, v169 op_sel_hi:[0,0,0]
	v_mfma_scale_f32_16x16x128_f8f6f4 v[112:115], v[16:23], v[198:205], v[112:115], v169, v169 op_sel_hi:[0,0,0]
	v_mfma_scale_f32_16x16x128_f8f6f4 v[108:111], v[24:31], v[198:205], v[108:111], v169, v169 op_sel_hi:[0,0,0]
	s_setprio 0
	s_setprio 1
	v_mfma_scale_f32_16x16x128_f8f6f4 v[152:155], v[0:7], v[224:231], v[152:155], v169, v169 op_sel_hi:[0,0,0]
	v_mfma_scale_f32_16x16x128_f8f6f4 v[148:151], v[8:15], v[224:231], v[148:151], v169, v169 op_sel_hi:[0,0,0]
	v_mfma_scale_f32_16x16x128_f8f6f4 v[136:139], v[0:7], v[232:239], v[136:139], v169, v169 op_sel_hi:[0,0,0]
	v_mfma_scale_f32_16x16x128_f8f6f4 v[132:135], v[8:15], v[232:239], v[132:135], v169, v169 op_sel_hi:[0,0,0]
	v_mfma_scale_f32_16x16x128_f8f6f4 v[120:123], v[0:7], v[240:247], v[120:123], v169, v169 op_sel_hi:[0,0,0]
	v_mfma_scale_f32_16x16x128_f8f6f4 v[116:119], v[8:15], v[240:247], v[116:119], v169, v169 op_sel_hi:[0,0,0]
	v_mfma_scale_f32_16x16x128_f8f6f4 v[104:107], v[0:7], v[198:205], v[104:107], v169, v169 op_sel_hi:[0,0,0]
	v_mfma_scale_f32_16x16x128_f8f6f4 v[100:103], v[8:15], v[198:205], v[100:103], v169, v169 op_sel_hi:[0,0,0]
	s_setprio 0
	s_barrier
	s_mov_b32 m0, s54
	v_lshl_add_u64 v[182:183], s[22:23], 0, v[172:173]
	s_add_u32 vcc_lo, s22, 0x4000
	ds_read_b128 v[198:201], v222 offset:16384
	ds_read_b128 v[202:205], v222 offset:17408
	ds_read_b128 v[224:227], v222 offset:18432
	ds_read_b128 v[228:231], v222 offset:19456
	ds_read_b128 v[232:235], v222 offset:20480
	ds_read_b128 v[236:239], v222 offset:21504
	ds_read_b128 v[240:243], v222 offset:22528
	ds_read_b128 v[244:247], v222 offset:23552
	global_load_lds_dwordx4 v[182:183], off
	v_lshl_add_u64 v[182:183], s[22:23], 0, v[174:175]
	s_mov_b32 m0, s55
	s_addc_u32 vcc_hi, s23, 0
	global_load_lds_dwordx4 v[182:183], off
	v_lshl_add_u64 v[182:183], vcc, 0, v[172:173]
	s_mov_b32 m0, s56
	v_mov_b32_e32 v177, v33
	global_load_lds_dwordx4 v[182:183], off
	v_lshl_add_u64 v[182:183], vcc, 0, v[174:175]
	s_mov_b32 m0, s57
	v_lshl_add_u64 v[184:185], s[26:27], 0, v[32:33]
	global_load_lds_dwordx4 v[182:183], off
	s_mov_b32 m0, s47
	v_lshl_add_u64 v[182:183], s[26:27], 0, v[176:177]
	global_load_lds_dwordx4 v32, s[26:27]
	s_mov_b32 m0, s58
	s_nop 0
	global_load_lds_dwordx4 v176, s[26:27]
	s_cmp_lg_i32 s71, -2
	s_cbranch_scc1 .Lgw1_steady
	s_cmp_eq_u32 s95, 0
	s_cbranch_scc1 .Lgw1_steady
	s_waitcnt vmcnt(24)
	s_branch .Lgw1_done

; #define PG8_STAGE(bufoff, gbase, voff) do { _Pragma("unroll") for (int _i = 0; _i < 2; ++_i) \
;         __builtin_amdgcn_global_load_lds((const unsigned*)((const char*)(gbase) + (voff)[_i]), (LAS unsigned*)(lds + (bufoff) + ldsw + _i * 8192), 16, 0, 0); } while (0)
; #define PG8_WAIT_V(n) asm volatile("s_waitcnt vmcnt(" #n ")" ::: "memory")
; #define PG8_WAIT_L(n) asm volatile("s_waitcnt lgkmcnt(" #n ")" ::: "memory")
; #define PG8_BAR __builtin_amdgcn_s_barrier()
; #define PG8_SCHED __builtin_amdgcn_sched_barrier(0)
; template <bool GATHER, bool FP8, class Epi, class Sched>
; __device__ __forceinline__ void gemm_phase(LAS unsigned char* lds, const int tid, const int K, const Sched& S, const Epi& E) {
;     ...
;             PG8_WAIT_V(8); PG8_WAIT_L(0); PG8_BAR; PG8_MMA(1, 0, At, B0); PG8_MMA(1, 1, At, B1); PG8_BAR; PG8_SCHED;
;             PG8_LDB(B0, 1, 0); PG8_LDB(B1, 1, 1); PG8_SCHED; PG8_LDA(At, 1, 0); PG8_STAGE(PG8_SA(0, 1), a2 + hsA, o2[1]);
;             PG8_WAIT_V(8); PG8_WAIT_L(0); PG8_BAR; PG8_MMA(0, 0, At, B0); PG8_MMA(0, 1, At, B1); PG8_BAR; PG8_SCHED;
.Lgw1_done:
	s_waitcnt lgkmcnt(0)
	s_barrier
	s_setprio 1
	s_waitcnt lgkmcnt(0)
	v_mfma_scale_f32_16x16x128_f8f6f4 v[96:99], v[16:23], v[198:205], v[96:99], v169, v169 op_sel_hi:[0,0,0]
	v_mfma_scale_f32_16x16x128_f8f6f4 v[92:95], v[24:31], v[198:205], v[92:95], v169, v169 op_sel_hi:[0,0,0]
	v_mfma_scale_f32_16x16x128_f8f6f4 v[80:83], v[16:23], v[224:231], v[80:83], v169, v169 op_sel_hi:[0,0,0]
	v_mfma_scale_f32_16x16x128_f8f6f4 v[76:79], v[24:31], v[224:231], v[76:79], v169, v169 op_sel_hi:[0,0,0]
	v_mfma_scale_f32_16x16x128_f8f6f4 v[64:67], v[16:23], v[232:239], v[64:67], v169, v169 op_sel_hi:[0,0,0]
	v_mfma_scale_f32_16x16x128_f8f6f4 v[60:63], v[24:31], v[232:239], v[60:63], v169, v169 op_sel_hi:[0,0,0]
	v_mfma_scale_f32_16x16x128_f8f6f4 v[48:51], v[16:23], v[240:247], v[48:51], v169, v169 op_sel_hi:[0,0,0]
	v_mfma_scale_f32_16x16x128_f8f6f4 v[44:47], v[24:31], v[240:247], v[44:47], v169, v169 op_sel_hi:[0,0,0]
	s_setprio 0
	s_setprio 1
	v_mfma_scale_f32_16x16x128_f8f6f4 v[88:91], v[0:7], v[198:205], v[88:91], v169, v169 op_sel_hi:[0,0,0]
	v_mfma_scale_f32_16x16x128_f8f6f4 v[84:87], v[8:15], v[198:205], v[84:87], v169, v169 op_sel_hi:[0,0,0]
	v_mfma_scale_f32_16x16x128_f8f6f4 v[72:75], v[0:7], v[224:231], v[72:75], v169, v169 op_sel_hi:[0,0,0]
	v_mfma_scale_f32_16x16x128_f8f6f4 v[68:71], v[8:15], v[224:231], v[68:71], v169, v169 op_sel_hi:[0,0,0]
	v_mfma_scale_f32_16x16x128_f8f6f4 v[56:59], v[0:7], v[232:239], v[56:59], v169, v169 op_sel_hi:[0,0,0]
	v_mfma_scale_f32_16x16x128_f8f6f4 v[52:55], v[8:15], v[232:239], v[52:55], v169, v169 op_sel_hi:[0,0,0]
	v_mfma_scale_f32_16x16x128_f8f6f4 v[40:43], v[0:7], v[240:247], v[40:43], v169, v169 op_sel_hi:[0,0,0]
	v_mfma_scale_f32_16x16x128_f8f6f4 v[34:37], v[8:15], v[240:247], v[34:37], v169, v169 op_sel_hi:[0,0,0]
	s_setprio 0
	s_barrier
	ds_read_b128 v[0:3], v214
	ds_read_b128 v[4:7], v215
	ds_read_b128 v[8:11], v216
	ds_read_b128 v[12:15], v217
	ds_read_b128 v[16:19], v218
	ds_read_b128 v[20:23], v219
	ds_read_b128 v[24:27], v220
	ds_read_b128 v[28:31], v221
	s_mov_b32 m0, s59
	ds_read_b128 v[198:201], v222 offset:32768
	ds_read_b128 v[202:205], v222 offset:33792
	ds_read_b128 v[224:227], v222 offset:34816
	ds_read_b128 v[228:231], v222 offset:35840
	ds_read_b128 v[232:235], v222 offset:36864
	ds_read_b128 v[236:239], v222 offset:37888
	ds_read_b128 v[240:243], v222 offset:38912
	ds_read_b128 v[244:247], v222 offset:39936
	global_load_lds_dwordx4 v188, s[26:27]
	s_mov_b32 m0, s60
	s_nop 0
	global_load_lds_dwordx4 v190, s[26:27]
	s_waitcnt vmcnt(8)
	s_waitcnt lgkmcnt(0)
	s_barrier
	s_setprio 1
	s_waitcnt lgkmcnt(0)
	v_mfma_scale_f32_16x16x128_f8f6f4 v[160:163], v[0:7], v[198:205], v[160:163], v169, v169 op_sel_hi:[0,0,0]
	v_mfma_scale_f32_16x16x128_f8f6f4 v[156:159], v[8:15], v[198:205], v[156:159], v169, v169 op_sel_hi:[0,0,0]
	v_mfma_scale_f32_16x16x128_f8f6f4 v[144:147], v[0:7], v[224:231], v[144:147], v169, v169 op_sel_hi:[0,0,0]
	v_mfma_scale_f32_16x16x128_f8f6f4 v[140:143], v[8:15], v[224:231], v[140:143], v169, v169 op_sel_hi:[0,0,0]
	v_mfma_scale_f32_16x16x128_f8f6f4 v[128:131], v[0:7], v[232:239], v[128:131], v169, v169 op_sel_hi:[0,0,0]
	v_mfma_scale_f32_16x16x128_f8f6f4 v[124:127], v[8:15], v[232:239], v[124:127], v169, v169 op_sel_hi:[0,0,0]
	v_mfma_scale_f32_16x16x128_f8f6f4 v[112:115], v[0:7], v[240:247], v[112:115], v169, v169 op_sel_hi:[0,0,0]
	v_mfma_scale_f32_16x16x128_f8f6f4 v[108:111], v[8:15], v[240:247], v[108:111], v169, v169 op_sel_hi:[0,0,0]
	s_setprio 0
	s_setprio 1
	v_mfma_scale_f32_16x16x128_f8f6f4 v[152:155], v[16:23], v[198:205], v[152:155], v169, v169 op_sel_hi:[0,0,0]
	v_mfma_scale_f32_16x16x128_f8f6f4 v[148:151], v[24:31], v[198:205], v[148:151], v169, v169 op_sel_hi:[0,0,0]
	v_mfma_scale_f32_16x16x128_f8f6f4 v[136:139], v[16:23], v[224:231], v[136:139], v169, v169 op_sel_hi:[0,0,0]
	v_mfma_scale_f32_16x16x128_f8f6f4 v[132:135], v[24:31], v[224:231], v[132:135], v169, v169 op_sel_hi:[0,0,0]
	v_mfma_scale_f32_16x16x128_f8f6f4 v[120:123], v[16:23], v[232:239], v[120:123], v169, v169 op_sel_hi:[0,0,0]
	v_mfma_scale_f32_16x16x128_f8f6f4 v[116:119], v[24:31], v[232:239], v[116:119], v169, v169 op_sel_hi:[0,0,0]
	v_mfma_scale_f32_16x16x128_f8f6f4 v[104:107], v[16:23], v[240:247], v[104:107], v169, v169 op_sel_hi:[0,0,0]
	v_mfma_scale_f32_16x16x128_f8f6f4 v[100:103], v[24:31], v[240:247], v[100:103], v169, v169 op_sel_hi:[0,0,0]
	s_setprio 0
	s_barrier
; #define PG8_STAGE(bufoff, gbase, voff) do { _Pragma("unroll") for (int _i = 0; _i < 2; ++_i) \
;         __builtin_amdgcn_global_load_lds((const unsigned*)((const char*)(gbase) + (voff)[_i]), (LAS unsigned*)(lds + (bufoff) + ldsw + _i * 8192), 16, 0, 0); } while (0)
; #define PG8_WAIT_V(n) asm volatile("s_waitcnt vmcnt(" #n ")" ::: "memory")
; #define PG8_WAIT_L(n) asm volatile("s_waitcnt lgkmcnt(" #n ")" ::: "memory")
; #define PG8_BAR __builtin_amdgcn_s_barrier()
; #define PG8_SCHED __builtin_amdgcn_sched_barrier(0)
; template <bool GATHER, bool FP8, class Epi, class Sched>
; __device__ __forceinline__ void gemm_phase(LAS unsigned char* lds, const int tid, const int K, const Sched& S, const Epi& E) {
;     ...
;             PG8_WAIT_V(8); PG8_WAIT_L(0); PG8_BAR; PG8_MMA(0, 0, At, B0); PG8_MMA(0, 1, At, B1); PG8_BAR; PG8_SCHED;
;             PG8_LDA(At, 1, 1); PG8_STAGE(PG8_SB(1, 0), b3, voffB); PG8_STAGE(PG8_SB(1, 1), b3 + hstepB, voffB); PG8_STAGE(PG8_SA(1, 0), a3, o2[0]);
;             PG8_WAIT_V(8); PG8_WAIT_L(0); PG8_BAR; PG8_MMA(1, 0, At, B0); PG8_MMA(1, 1, At, B1); PG8_BAR; PG8_SCHED;
;         }
	s_add_u32 s26, s22, 0x8000
	s_addc_u32 s27, s23, 0
	s_mov_b32 m0, s62
	v_lshl_add_u64 v[164:165], s[26:27], 0, v[172:173]
	s_add_u32 s22, s22, 0xc000
	ds_read_b128 v[198:201], v222 offset:49152
	ds_read_b128 v[202:205], v222 offset:50176
	ds_read_b128 v[224:227], v222 offset:51200
	ds_read_b128 v[228:231], v222 offset:52224
	ds_read_b128 v[232:235], v222 offset:53248
	ds_read_b128 v[236:239], v222 offset:54272
	ds_read_b128 v[240:243], v222 offset:55296
	ds_read_b128 v[244:247], v222 offset:56320
	global_load_lds_dwordx4 v[164:165], off
	v_lshl_add_u64 v[164:165], s[26:27], 0, v[174:175]
	s_mov_b32 m0, s63
	s_addc_u32 s23, s23, 0
	global_load_lds_dwordx4 v[164:165], off
	v_lshl_add_u64 v[164:165], s[22:23], 0, v[172:173]
	s_mov_b32 m0, s66
	s_nop 0
	global_load_lds_dwordx4 v[164:165], off
	v_lshl_add_u64 v[164:165], s[22:23], 0, v[174:175]
	s_mov_b32 m0, s67
	s_nop 0
	global_load_lds_dwordx4 v[164:165], off
	v_lshl_add_u64 v[164:165], v[184:185], 0, s[24:25]
	s_mov_b32 m0, s64
	s_nop 0
	global_load_lds_dwordx4 v[164:165], off
	v_lshl_add_u64 v[164:165], v[182:183], 0, s[24:25]
	s_mov_b32 m0, s65
	s_nop 0
	global_load_lds_dwordx4 v[164:165], off
	s_waitcnt vmcnt(8)
	s_waitcnt lgkmcnt(0)
	s_barrier
	s_setprio 1
	s_waitcnt lgkmcnt(0)
	v_mfma_scale_f32_16x16x128_f8f6f4 v[96:99], v[0:7], v[198:205], v[96:99], v169, v169 op_sel_hi:[0,0,0]
	v_mfma_scale_f32_16x16x128_f8f6f4 v[92:95], v[8:15], v[198:205], v[92:95], v169, v169 op_sel_hi:[0,0,0]
	v_mfma_scale_f32_16x16x128_f8f6f4 v[80:83], v[0:7], v[224:231], v[80:83], v169, v169 op_sel_hi:[0,0,0]
	v_mfma_scale_f32_16x16x128_f8f6f4 v[76:79], v[8:15], v[224:231], v[76:79], v169, v169 op_sel_hi:[0,0,0]
	v_mfma_scale_f32_16x16x128_f8f6f4 v[64:67], v[0:7], v[232:239], v[64:67], v169, v169 op_sel_hi:[0,0,0]
	v_mfma_scale_f32_16x16x128_f8f6f4 v[60:63], v[8:15], v[232:239], v[60:63], v169, v169 op_sel_hi:[0,0,0]
	v_mfma_scale_f32_16x16x128_f8f6f4 v[48:51], v[0:7], v[240:247], v[48:51], v169, v169 op_sel_hi:[0,0,0]
	v_mfma_scale_f32_16x16x128_f8f6f4 v[44:47], v[8:15], v[240:247], v[44:47], v169, v169 op_sel_hi:[0,0,0]
	s_setprio 0
	s_setprio 1
	v_mfma_scale_f32_16x16x128_f8f6f4 v[88:91], v[16:23], v[198:205], v[88:91], v169, v169 op_sel_hi:[0,0,0]
	v_mfma_scale_f32_16x16x128_f8f6f4 v[84:87], v[24:31], v[198:205], v[84:87], v169, v169 op_sel_hi:[0,0,0]
	v_mfma_scale_f32_16x16x128_f8f6f4 v[72:75], v[16:23], v[224:231], v[72:75], v169, v169 op_sel_hi:[0,0,0]
	v_mfma_scale_f32_16x16x128_f8f6f4 v[68:71], v[24:31], v[224:231], v[68:71], v169, v169 op_sel_hi:[0,0,0]
	v_mfma_scale_f32_16x16x128_f8f6f4 v[56:59], v[16:23], v[232:239], v[56:59], v169, v169 op_sel_hi:[0,0,0]
	v_mfma_scale_f32_16x16x128_f8f6f4 v[52:55], v[24:31], v[232:239], v[52:55], v169, v169 op_sel_hi:[0,0,0]
	v_mfma_scale_f32_16x16x128_f8f6f4 v[40:43], v[16:23], v[240:247], v[40:43], v169, v169 op_sel_hi:[0,0,0]
	v_mfma_scale_f32_16x16x128_f8f6f4 v[34:37], v[24:31], v[240:247], v[34:37], v169, v169 op_sel_hi:[0,0,0]
	s_setprio 0
	s_barrier
	s_add_i32 s71, s71, 2
	s_add_u32 s17, s17, 0x10000
	s_addc_u32 s12, s12, 0
	s_add_u32 s20, s20, 0x100
	s_addc_u32 s21, s21, 0
	s_cmp_gt_u32 s71, 5
	s_cbranch_scc1 .LBB0_99
